# GLU epilogue stores write-through + P5|P6 seam reduced to the 4-workgroup group sync (no L2 write-back needed there)
# speedup vs baseline: 1.0126x; 1.0014x over previous
; __device__ __forceinline__ unsigned pk2(float lo, float hi) { f32x2 v = {lo, hi}; bf2_t b = __builtin_convertvector(v, bf2_t); return __builtin_bit_cast(unsigned, b); }
; __device__ __forceinline__ float ex2(float x) { return __builtin_amdgcn_exp2f(x); }
; __device__ __forceinline__ float rcpf(float x) { return __builtin_amdgcn_rcpf(x); }
;     __device__ __forceinline__ void operator()(const f32x4 (&acc)[2][2][4][2], const Unit& u, int wr, int wc, int fr, int fq) const {
;     ...
;                     const int c = u.pn * 256 + bj * 128 + wc * 32 + 8 * fq;
;                     const f32x4 v0 = acc[ai][bj][m][0], v1 = acc[ai][bj][m][1];
;                     const float o0 = v0[0] * rcpf(1.0f + ex2(-LOG2E * v0[1])), o1 = v0[2] * rcpf(1.0f + ex2(-LOG2E * v0[3]));
;                     const float o2 = v1[0] * rcpf(1.0f + ex2(-LOG2E * v1[1])), o3 = v1[2] * rcpf(1.0f + ex2(-LOG2E * v1[3]));
;                     u32x2 w; w.x = pk2(o0, o1); w.y = pk2(o2, o3);
;                     *(u32x2*)(MIX + (size_t)row * 1024 + 512 + (c >> 1)) = w;
.LBB0_622:
	v_mul_f32_e32 v125, 0xbfb8aa3b, v125
	v_exp_f32_e32 v125, v125
	v_mul_f32_e32 v121, 0xbfb8aa3b, v121
	v_exp_f32_e32 v121, v121
	v_mul_f32_e32 v117, 0xbfb8aa3b, v117
	v_add_f32_e32 v125, 1.0, v125
	v_rcp_f32_e32 v146, v125
	v_mul_f32_e32 v125, 0xbfb8aa3b, v127
	v_exp_f32_e32 v125, v125
	v_add_f32_e32 v121, 1.0, v121
	v_lshl_add_u32 v138, s22, 8, v140
	v_lshl_or_b32 v148, s58, 8, v142
	v_add_f32_e32 v125, 1.0, v125
	v_rcp_f32_e32 v147, v125
	v_mov_b32_e32 v125, v126
	v_rcp_f32_e32 v126, v121
	v_mul_f32_e32 v121, 0xbfb8aa3b, v123
	v_exp_f32_e32 v121, v121
	v_exp_f32_e32 v117, v117
	v_ashrrev_i32_e32 v139, 31, v138
	v_lshlrev_b64 v[144:145], 11, v[138:139]
	v_add_f32_e32 v121, 1.0, v121
	v_rcp_f32_e32 v127, v121
	v_mov_b32_e32 v121, v122
	v_ashrrev_i32_e32 v122, 1, v148
	v_pk_mul_f32 v[124:125], v[124:125], v[146:147]
	v_pk_mul_f32 v[120:121], v[120:121], v[126:127]
	v_ashrrev_i32_e32 v123, 31, v122
	v_cvt_pk_bf16_f32 v124, v124, v125
	v_cvt_pk_bf16_f32 v125, v120, v121
	v_lshl_add_u64 v[120:121], s[16:17], 0, v[144:145]
	v_lshlrev_b64 v[122:123], 1, v[122:123]
	v_lshl_add_u64 v[120:121], v[120:121], 0, v[122:123]
	v_add_f32_e32 v117, 1.0, v117
	flat_store_dwordx2 v[120:121], v[124:125] offset:1024 sc1
	v_rcp_f32_e32 v124, v117
	v_mul_f32_e32 v117, 0xbfb8aa3b, v119
	v_mul_f32_e32 v113, 0xbfb8aa3b, v113
	v_exp_f32_e32 v117, v117
	v_exp_f32_e32 v113, v113
	v_mul_f32_e32 v109, 0xbfb8aa3b, v109
	v_exp_f32_e32 v109, v109
	v_add_f32_e32 v117, 1.0, v117
	v_add_f32_e32 v113, 1.0, v113
	v_rcp_f32_e32 v125, v117
	v_mov_b32_e32 v117, v118
	v_rcp_f32_e32 v118, v113
	v_mul_f32_e32 v113, 0xbfb8aa3b, v115
	v_exp_f32_e32 v113, v113
	v_pk_mul_f32 v[116:117], v[116:117], v[124:125]
	v_add_f32_e32 v109, 1.0, v109
	v_mul_f32_e32 v105, 0xbfb8aa3b, v105
	v_add_f32_e32 v113, 1.0, v113
	v_rcp_f32_e32 v119, v113
	v_mov_b32_e32 v113, v114
	v_cvt_pk_bf16_f32 v114, v116, v117
	v_exp_f32_e32 v105, v105
	v_pk_mul_f32 v[112:113], v[112:113], v[118:119]
	v_mul_f32_e32 v101, 0xbfb8aa3b, v101
	v_cvt_pk_bf16_f32 v115, v112, v113
	flat_store_dwordx2 v[120:121], v[114:115] offset:1152 sc1
	v_rcp_f32_e32 v114, v109
	v_mul_f32_e32 v109, 0xbfb8aa3b, v111
	v_exp_f32_e32 v109, v109
	v_add_f32_e32 v105, 1.0, v105
	v_or_b32_e32 v112, 16, v138
	v_exp_f32_e32 v101, v101
	v_add_f32_e32 v109, 1.0, v109
	v_rcp_f32_e32 v115, v109
	v_mov_b32_e32 v109, v110
	v_rcp_f32_e32 v110, v105
	v_mul_f32_e32 v105, 0xbfb8aa3b, v107
	v_exp_f32_e32 v105, v105
	v_ashrrev_i32_e32 v113, 31, v112
	v_lshlrev_b64 v[112:113], 11, v[112:113]
	v_pk_mul_f32 v[108:109], v[108:109], v[114:115]
	v_add_f32_e32 v105, 1.0, v105
	v_rcp_f32_e32 v111, v105
	v_mov_b32_e32 v105, v106
	v_cvt_pk_bf16_f32 v106, v108, v109
	v_add_f32_e32 v101, 1.0, v101
	v_pk_mul_f32 v[104:105], v[104:105], v[110:111]
	v_mul_f32_e32 v97, 0xbfb8aa3b, v97
	v_cvt_pk_bf16_f32 v107, v104, v105
	v_lshl_add_u64 v[104:105], s[16:17], 0, v[112:113]
	v_lshl_add_u64 v[104:105], v[104:105], 0, v[122:123]
	flat_store_dwordx2 v[104:105], v[106:107] offset:1024 sc1
	v_rcp_f32_e32 v106, v101
	v_mul_f32_e32 v101, 0xbfb8aa3b, v103
	v_exp_f32_e32 v101, v101
	v_exp_f32_e32 v97, v97
	v_mul_f32_e32 v93, 0xbfb8aa3b, v93
	v_exp_f32_e32 v93, v93
	v_add_f32_e32 v101, 1.0, v101
	v_add_f32_e32 v97, 1.0, v97
	v_rcp_f32_e32 v107, v101
	v_mov_b32_e32 v101, v102
	v_rcp_f32_e32 v102, v97
	v_mul_f32_e32 v97, 0xbfb8aa3b, v99
	v_exp_f32_e32 v97, v97
	v_pk_mul_f32 v[100:101], v[100:101], v[106:107]
	v_add_f32_e32 v93, 1.0, v93
	v_mul_f32_e32 v89, 0xbfb8aa3b, v89
	v_add_f32_e32 v97, 1.0, v97
	v_rcp_f32_e32 v103, v97
	v_mov_b32_e32 v97, v98
	v_cvt_pk_bf16_f32 v98, v100, v101
	v_exp_f32_e32 v89, v89
	v_pk_mul_f32 v[96:97], v[96:97], v[102:103]
	v_mul_f32_e32 v85, 0xbfb8aa3b, v85
	v_cvt_pk_bf16_f32 v99, v96, v97
	flat_store_dwordx2 v[104:105], v[98:99] offset:1152 sc1
	v_rcp_f32_e32 v98, v93
	v_mul_f32_e32 v93, 0xbfb8aa3b, v95
	v_exp_f32_e32 v93, v93
	v_add_f32_e32 v89, 1.0, v89
	v_or_b32_e32 v96, 32, v138
	v_exp_f32_e32 v85, v85
	v_add_f32_e32 v93, 1.0, v93
	v_rcp_f32_e32 v99, v93
	v_mov_b32_e32 v93, v94
	v_rcp_f32_e32 v94, v89
	v_mul_f32_e32 v89, 0xbfb8aa3b, v91
	v_exp_f32_e32 v89, v89
	v_ashrrev_i32_e32 v97, 31, v96
	v_lshlrev_b64 v[96:97], 11, v[96:97]
	v_pk_mul_f32 v[92:93], v[92:93], v[98:99]
	v_add_f32_e32 v89, 1.0, v89
	v_rcp_f32_e32 v95, v89
	v_mov_b32_e32 v89, v90
	v_cvt_pk_bf16_f32 v90, v92, v93
	v_add_f32_e32 v85, 1.0, v85
	v_pk_mul_f32 v[88:89], v[88:89], v[94:95]
	v_mul_f32_e32 v81, 0xbfb8aa3b, v81
	v_cvt_pk_bf16_f32 v91, v88, v89
	v_lshl_add_u64 v[88:89], s[16:17], 0, v[96:97]
	v_lshl_add_u64 v[88:89], v[88:89], 0, v[122:123]
	flat_store_dwordx2 v[88:89], v[90:91] offset:1024 sc1
	v_rcp_f32_e32 v90, v85
	v_mul_f32_e32 v85, 0xbfb8aa3b, v87
	v_exp_f32_e32 v85, v85
	v_exp_f32_e32 v81, v81
	v_mul_f32_e32 v77, 0xbfb8aa3b, v77
	v_exp_f32_e32 v77, v77
	v_add_f32_e32 v85, 1.0, v85
	v_add_f32_e32 v81, 1.0, v81
	v_rcp_f32_e32 v91, v85
	v_mov_b32_e32 v85, v86
	v_rcp_f32_e32 v86, v81
	v_mul_f32_e32 v81, 0xbfb8aa3b, v83
	v_exp_f32_e32 v81, v81
	v_pk_mul_f32 v[84:85], v[84:85], v[90:91]
	v_add_f32_e32 v77, 1.0, v77
	v_mul_f32_e32 v73, 0xbfb8aa3b, v73
	v_add_f32_e32 v81, 1.0, v81
	v_rcp_f32_e32 v87, v81
	v_mov_b32_e32 v81, v82
	v_cvt_pk_bf16_f32 v82, v84, v85
	v_exp_f32_e32 v73, v73
	v_pk_mul_f32 v[80:81], v[80:81], v[86:87]
	v_mul_f32_e32 v69, 0xbfb8aa3b, v69
	v_cvt_pk_bf16_f32 v83, v80, v81
	flat_store_dwordx2 v[88:89], v[82:83] offset:1152 sc1
	v_rcp_f32_e32 v82, v77
	v_mul_f32_e32 v77, 0xbfb8aa3b, v79
	v_exp_f32_e32 v77, v77
	v_add_f32_e32 v73, 1.0, v73
	v_or_b32_e32 v80, 48, v138
	v_exp_f32_e32 v69, v69
	v_add_f32_e32 v77, 1.0, v77
	v_rcp_f32_e32 v83, v77
; __device__ __forceinline__ unsigned pk2(float lo, float hi) { f32x2 v = {lo, hi}; bf2_t b = __builtin_convertvector(v, bf2_t); return __builtin_bit_cast(unsigned, b); }
; __device__ __forceinline__ float ex2(float x) { return __builtin_amdgcn_exp2f(x); }
; __device__ __forceinline__ float rcpf(float x) { return __builtin_amdgcn_rcpf(x); }
;     __device__ __forceinline__ void operator()(const f32x4 (&acc)[2][2][4][2], const Unit& u, int wr, int wc, int fr, int fq) const {
;     ...
;                     const int c = u.pn * 256 + bj * 128 + wc * 32 + 8 * fq;
;                     const f32x4 v0 = acc[ai][bj][m][0], v1 = acc[ai][bj][m][1];
;                     const float o0 = v0[0] * rcpf(1.0f + ex2(-LOG2E * v0[1])), o1 = v0[2] * rcpf(1.0f + ex2(-LOG2E * v0[3]));
;                     const float o2 = v1[0] * rcpf(1.0f + ex2(-LOG2E * v1[1])), o3 = v1[2] * rcpf(1.0f + ex2(-LOG2E * v1[3]));
;                     u32x2 w; w.x = pk2(o0, o1); w.y = pk2(o2, o3);
;                     *(u32x2*)(MIX + (size_t)row * 1024 + 512 + (c >> 1)) = w;
	v_mov_b32_e32 v77, v78
	v_rcp_f32_e32 v78, v73
	v_mul_f32_e32 v73, 0xbfb8aa3b, v75
	v_exp_f32_e32 v73, v73
	v_ashrrev_i32_e32 v81, 31, v80
	v_lshlrev_b64 v[80:81], 11, v[80:81]
	v_pk_mul_f32 v[76:77], v[76:77], v[82:83]
	v_add_f32_e32 v73, 1.0, v73
	v_rcp_f32_e32 v79, v73
	v_mov_b32_e32 v73, v74
	v_cvt_pk_bf16_f32 v74, v76, v77
	v_add_f32_e32 v69, 1.0, v69
	v_pk_mul_f32 v[72:73], v[72:73], v[78:79]
	v_mul_f32_e32 v65, 0xbfb8aa3b, v65
	v_cvt_pk_bf16_f32 v75, v72, v73
	v_lshl_add_u64 v[72:73], s[16:17], 0, v[80:81]
	v_lshl_add_u64 v[72:73], v[72:73], 0, v[122:123]
	flat_store_dwordx2 v[72:73], v[74:75] offset:1024 sc1
	v_rcp_f32_e32 v74, v69
	v_mul_f32_e32 v69, 0xbfb8aa3b, v71
	v_exp_f32_e32 v69, v69
	v_exp_f32_e32 v65, v65
	v_mul_f32_e32 v61, 0xbfb8aa3b, v61
	v_exp_f32_e32 v61, v61
	v_add_f32_e32 v69, 1.0, v69
	v_add_f32_e32 v65, 1.0, v65
	v_rcp_f32_e32 v75, v69
	v_mov_b32_e32 v69, v70
	v_rcp_f32_e32 v70, v65
	v_mul_f32_e32 v65, 0xbfb8aa3b, v67
	v_exp_f32_e32 v65, v65
	v_add_f32_e32 v61, 1.0, v61
	v_mul_f32_e32 v57, 0xbfb8aa3b, v57
	v_exp_f32_e32 v57, v57
	v_add_f32_e32 v65, 1.0, v65
	v_rcp_f32_e32 v71, v65
	v_mov_b32_e32 v65, v66
	v_add_f32_e32 v57, 1.0, v57
	v_mul_f32_e32 v53, 0xbfb8aa3b, v53
	v_pk_mul_f32 v[64:65], v[64:65], v[70:71]
	v_exp_f32_e32 v53, v53
	v_cvt_pk_bf16_f32 v67, v64, v65
	v_rcp_f32_e32 v64, v61
	v_mul_f32_e32 v61, 0xbfb8aa3b, v63
	v_exp_f32_e32 v61, v61
	v_add_f32_e32 v53, 1.0, v53
	v_mul_f32_e32 v49, 0xbfb8aa3b, v49
	v_exp_f32_e32 v49, v49
	v_add_f32_e32 v61, 1.0, v61
	v_rcp_f32_e32 v65, v61
	v_mov_b32_e32 v61, v62
	v_rcp_f32_e32 v62, v57
	v_mul_f32_e32 v57, 0xbfb8aa3b, v59
	v_exp_f32_e32 v57, v57
	v_pk_mul_f32 v[60:61], v[60:61], v[64:65]
	v_add_f32_e32 v49, 1.0, v49
	v_mul_f32_e32 v45, 0xbfb8aa3b, v45
	v_add_f32_e32 v57, 1.0, v57
	v_rcp_f32_e32 v63, v57
	v_mov_b32_e32 v57, v58
	v_cvt_pk_bf16_f32 v58, v60, v61
	v_exp_f32_e32 v45, v45
	v_pk_mul_f32 v[56:57], v[56:57], v[62:63]
	v_mul_f32_e32 v41, 0xbfb8aa3b, v41
	v_cvt_pk_bf16_f32 v59, v56, v57
	v_lshl_add_u64 v[56:57], v[120:121], 0, s[18:19]
	flat_store_dwordx2 v[56:57], v[58:59] offset:1024 sc1
	v_rcp_f32_e32 v58, v53
	v_mul_f32_e32 v53, 0xbfb8aa3b, v55
	v_exp_f32_e32 v53, v53
	v_add_f32_e32 v45, 1.0, v45
	v_exp_f32_e32 v41, v41
	v_mul_f32_e32 v37, 0xbfb8aa3b, v37
	v_add_f32_e32 v53, 1.0, v53
	v_rcp_f32_e32 v59, v53
	v_mov_b32_e32 v53, v54
	v_rcp_f32_e32 v54, v49
	v_mul_f32_e32 v49, 0xbfb8aa3b, v51
	v_exp_f32_e32 v49, v49
	v_add_f32_e32 v41, 1.0, v41
	v_exp_f32_e32 v37, v37
	v_mul_f32_e32 v33, 0xbfb8aa3b, v33
	v_add_f32_e32 v49, 1.0, v49
	v_rcp_f32_e32 v55, v49
	v_mov_b32_e32 v49, v50
	v_add_f32_e32 v37, 1.0, v37
	v_exp_f32_e32 v33, v33
	v_pk_mul_f32 v[48:49], v[48:49], v[54:55]
	v_mul_f32_e32 v29, 0xbfb8aa3b, v29
	v_cvt_pk_bf16_f32 v51, v48, v49
	v_rcp_f32_e32 v48, v45
	v_mul_f32_e32 v45, 0xbfb8aa3b, v47
	v_exp_f32_e32 v45, v45
	v_add_f32_e32 v33, 1.0, v33
	v_exp_f32_e32 v29, v29
	v_mul_f32_e32 v25, 0xbfb8aa3b, v25
	v_add_f32_e32 v45, 1.0, v45
	v_rcp_f32_e32 v49, v45
	v_mov_b32_e32 v45, v46
	v_rcp_f32_e32 v46, v41
	v_mul_f32_e32 v41, 0xbfb8aa3b, v43
	v_exp_f32_e32 v41, v41
	v_pk_mul_f32 v[44:45], v[44:45], v[48:49]
	v_add_f32_e32 v29, 1.0, v29
	v_exp_f32_e32 v25, v25
	v_add_f32_e32 v41, 1.0, v41
	v_rcp_f32_e32 v47, v41
	v_mov_b32_e32 v41, v42
	v_cvt_pk_bf16_f32 v42, v44, v45
	v_add_f32_e32 v25, 1.0, v25
	v_pk_mul_f32 v[40:41], v[40:41], v[46:47]
	v_mul_f32_e32 v21, 0xbfb8aa3b, v21
	v_cvt_pk_bf16_f32 v43, v40, v41
	v_lshl_add_u64 v[40:41], v[120:121], 0, s[64:65]
	flat_store_dwordx2 v[40:41], v[42:43] offset:1024 sc1
	v_rcp_f32_e32 v42, v37
; __device__ __forceinline__ unsigned pk2(float lo, float hi) { f32x2 v = {lo, hi}; bf2_t b = __builtin_convertvector(v, bf2_t); return __builtin_bit_cast(unsigned, b); }
; __device__ __forceinline__ float ex2(float x) { return __builtin_amdgcn_exp2f(x); }
; __device__ __forceinline__ float rcpf(float x) { return __builtin_amdgcn_rcpf(x); }
;     __device__ __forceinline__ void operator()(const f32x4 (&acc)[2][2][4][2], const Unit& u, int wr, int wc, int fr, int fq) const {
;     ...
;                 const int row = row0 + ai * 128 + m * 16;
; #pragma unroll
;                 for (int bj = 0; bj < 2; ++bj) {
;                     const int c = u.pn * 256 + bj * 128 + wc * 32 + 8 * fq;
;                     const f32x4 v0 = acc[ai][bj][m][0], v1 = acc[ai][bj][m][1];
;                     const float o0 = v0[0] * rcpf(1.0f + ex2(-LOG2E * v0[1])), o1 = v0[2] * rcpf(1.0f + ex2(-LOG2E * v0[3]));
;                     const float o2 = v1[0] * rcpf(1.0f + ex2(-LOG2E * v1[1])), o3 = v1[2] * rcpf(1.0f + ex2(-LOG2E * v1[3]));
;                     u32x2 w; w.x = pk2(o0, o1); w.y = pk2(o2, o3);
;                     *(u32x2*)(MIX + (size_t)row * 1024 + 512 + (c >> 1)) = w;
	v_mul_f32_e32 v37, 0xbfb8aa3b, v39
	v_exp_f32_e32 v37, v37
	v_exp_f32_e32 v21, v21
	v_mul_f32_e32 v17, 0xbfb8aa3b, v17
	v_exp_f32_e32 v17, v17
	v_add_f32_e32 v37, 1.0, v37
	v_rcp_f32_e32 v43, v37
	v_mov_b32_e32 v37, v38
	v_rcp_f32_e32 v38, v33
	v_mul_f32_e32 v33, 0xbfb8aa3b, v35
	v_exp_f32_e32 v33, v33
	v_add_f32_e32 v21, 1.0, v21
	v_add_f32_e32 v17, 1.0, v17
	v_mul_f32_e32 v13, 0xbfb8aa3b, v13
	v_add_f32_e32 v33, 1.0, v33
	v_rcp_f32_e32 v39, v33
	v_mov_b32_e32 v33, v34
	v_exp_f32_e32 v13, v13
	v_mul_f32_e32 v9, 0xbfb8aa3b, v9
	v_pk_mul_f32 v[32:33], v[32:33], v[38:39]
	v_exp_f32_e32 v9, v9
	v_cvt_pk_bf16_f32 v35, v32, v33
	v_rcp_f32_e32 v32, v29
	v_mul_f32_e32 v29, 0xbfb8aa3b, v31
	v_exp_f32_e32 v29, v29
	v_add_f32_e32 v13, 1.0, v13
	v_add_f32_e32 v9, 1.0, v9
	v_mul_f32_e32 v5, 0xbfb8aa3b, v5
	v_add_f32_e32 v29, 1.0, v29
	v_rcp_f32_e32 v33, v29
	v_mov_b32_e32 v29, v30
	v_rcp_f32_e32 v30, v25
	v_mul_f32_e32 v25, 0xbfb8aa3b, v27
	v_exp_f32_e32 v25, v25
	v_pk_mul_f32 v[28:29], v[28:29], v[32:33]
	v_exp_f32_e32 v5, v5
	v_mul_f32_e32 v1, 0xbfb8aa3b, v1
	v_add_f32_e32 v25, 1.0, v25
	v_rcp_f32_e32 v31, v25
	v_mov_b32_e32 v25, v26
	v_cvt_pk_bf16_f32 v26, v28, v29
	v_add_f32_e32 v5, 1.0, v5
	v_pk_mul_f32 v[24:25], v[24:25], v[30:31]
	v_exp_f32_e32 v1, v1
	v_cvt_pk_bf16_f32 v27, v24, v25
	v_lshl_add_u64 v[24:25], v[120:121], 0, s[66:67]
	flat_store_dwordx2 v[24:25], v[26:27] offset:1024 sc1
	v_rcp_f32_e32 v26, v21
	v_mul_f32_e32 v21, 0xbfb8aa3b, v23
	v_exp_f32_e32 v21, v21
	v_add_f32_e32 v1, 1.0, v1
	v_pk_mul_f32 v[68:69], v[68:69], v[74:75]
	v_pk_mul_f32 v[52:53], v[52:53], v[58:59]
	v_add_f32_e32 v21, 1.0, v21
	v_rcp_f32_e32 v27, v21
	v_mov_b32_e32 v21, v22
	v_rcp_f32_e32 v22, v17
	v_mul_f32_e32 v17, 0xbfb8aa3b, v19
	v_exp_f32_e32 v17, v17
	v_pk_mul_f32 v[36:37], v[36:37], v[42:43]
	v_pk_mul_f32 v[20:21], v[20:21], v[26:27]
	v_cvt_pk_bf16_f32 v66, v68, v69
	v_add_f32_e32 v17, 1.0, v17
	v_rcp_f32_e32 v23, v17
	v_mov_b32_e32 v17, v18
	v_cvt_pk_bf16_f32 v50, v52, v53
	v_cvt_pk_bf16_f32 v34, v36, v37
	v_pk_mul_f32 v[16:17], v[16:17], v[22:23]
	v_cvt_pk_bf16_f32 v18, v20, v21
	v_cvt_pk_bf16_f32 v19, v16, v17
	v_rcp_f32_e32 v16, v13
	v_mul_f32_e32 v13, 0xbfb8aa3b, v15
	v_exp_f32_e32 v13, v13
	s_mov_b64 s[10:11], -1
	s_andn2_b64 vcc, exec, s[38:39]
	flat_store_dwordx2 v[72:73], v[66:67] offset:1152 sc1
	v_add_f32_e32 v13, 1.0, v13
	v_rcp_f32_e32 v17, v13
	v_mov_b32_e32 v13, v14
	v_rcp_f32_e32 v14, v9
	v_mul_f32_e32 v9, 0xbfb8aa3b, v11
	v_exp_f32_e32 v9, v9
	v_pk_mul_f32 v[12:13], v[12:13], v[16:17]
	flat_store_dwordx2 v[56:57], v[50:51] offset:1152 sc1
	flat_store_dwordx2 v[40:41], v[34:35] offset:1152 sc1
	v_add_f32_e32 v9, 1.0, v9
	v_rcp_f32_e32 v15, v9
	v_mov_b32_e32 v9, v10
	v_cvt_pk_bf16_f32 v10, v12, v13
	flat_store_dwordx2 v[24:25], v[18:19] offset:1152 sc1
	v_pk_mul_f32 v[8:9], v[8:9], v[14:15]
	s_nop 0
	v_cvt_pk_bf16_f32 v11, v8, v9
	v_lshl_add_u64 v[8:9], v[120:121], 0, s[68:69]
	flat_store_dwordx2 v[8:9], v[10:11] offset:1024 sc1
	v_rcp_f32_e32 v10, v5
	v_mul_f32_e32 v5, 0xbfb8aa3b, v7
	v_exp_f32_e32 v5, v5
	s_nop 0
	v_add_f32_e32 v5, 1.0, v5
	v_rcp_f32_e32 v11, v5
	v_mov_b32_e32 v5, v6
	v_rcp_f32_e32 v6, v1
	v_mul_f32_e32 v1, 0xbfb8aa3b, v3
	v_exp_f32_e32 v1, v1
	v_pk_mul_f32 v[4:5], v[4:5], v[10:11]
	v_add_f32_e32 v1, 1.0, v1
	v_rcp_f32_e32 v7, v1
	v_mov_b32_e32 v1, v2
	v_cvt_pk_bf16_f32 v2, v4, v5
	v_pk_mul_f32 v[0:1], v[0:1], v[6:7]
	s_nop 0
	v_cvt_pk_bf16_f32 v3, v0, v1
	flat_store_dwordx2 v[8:9], v[2:3] offset:1152 sc1
	s_cbranch_vccnz .LBB0_611
	s_andn2_b64 vcc, exec, s[20:21]
	s_cbranch_vccnz .LBB0_610
	s_barrier
	s_branch .LBB0_610

; __device__ __forceinline__ unsigned xb_ld(unsigned* p)              { return __hip_atomic_load(p, __ATOMIC_RELAXED, __HIP_MEMORY_SCOPE_AGENT); }
; __device__ __forceinline__ unsigned xb_add(unsigned* p, unsigned v) { return __hip_atomic_fetch_add(p, v, __ATOMIC_RELAXED, __HIP_MEMORY_SCOPE_AGENT); }
; #define XB_SPIN(cond, bar) do { unsigned _sp = 0; while (cond) { __builtin_amdgcn_s_sleep(1); \
;     if ((++_sp & 255u) == 0u) { if (xb_ld(&(bar)[XB_TMO])) break; if (_sp > XB_SPIN_CAP) { atomicAdd(&(bar)[XB_TMO], 1u); break; } } } } while (0)
; __device__ __forceinline__ void xcd_barrier(const XcdBarrier& b) {
;     asm volatile("s_waitcnt vmcnt(0)" ::: "memory");
;     __syncthreads();
;     if (threadIdx.x == 0) {
;         unsigned* bar = b.bar;
;         __builtin_amdgcn_s_waitcnt(0);
;         unsigned nloc = b.st[0], nx = b.st[1];
;         if (nloc == 0u) { xcd_barrier_complete(bar, b.x, nloc, nx); b.st[0] = nloc; b.st[1] = nx; }
;         const unsigned old = xb_add(&bar[XB_XSUB(b.x)], 1u);
;         const unsigned gen = old / nloc;
;         if (old + 1u == (gen + 1u) * nloc) {
;             __builtin_amdgcn_fence(__ATOMIC_RELEASE, "agent");
;             asm volatile("s_waitcnt vmcnt(0)" ::: "memory");
;             const unsigned og = xb_add(&bar[XB_TOP], 1u);
;             const unsigned tg = og / nx;
;             __builtin_amdgcn_fence(__ATOMIC_ACQUIRE, "agent");
;             if (og + 1u == (tg + 1u) * nx) xb_add(&bar[XB_TOPGEN], 1u);
;             else XB_SPIN(xb_ld(&bar[XB_TOPGEN]) == tg, bar);
;             xb_add(&bar[XB_XGEN(b.x)], 1u);
.LBB0_626:
	s_waitcnt vmcnt(0)
	s_waitcnt vmcnt(0) lgkmcnt(0)
	s_barrier
	s_mov_b64 s[4:5], exec
	v_readlane_b32 s8, v253, 41
	v_readlane_b32 s9, v253, 42
	s_and_b64 s[8:9], s[4:5], s[8:9]
	s_mov_b64 exec, s[8:9]
	s_cbranch_execz .LBB0_678
	s_waitcnt vmcnt(0) lgkmcnt(0)
	v_readlane_b32 s8, v254, 29
	v_readlane_b32 s9, v254, 30
	v_readlane_b32 s20, v253, 0
	v_readlane_b32 s22, v254, 53
	s_add_u32 s8, s8, 0x6c00
	s_addc_u32 s9, s9, 0
	s_and_b32 s20, s20, 63
	s_lshl_b32 s20, s20, 8
	s_add_u32 s22, s22, 1
	s_lshl_b32 s22, s22, 2
	v_mov_b32_e32 v0, s20
	v_mov_b32_e32 v1, 1
	s_mov_b32 s25, 0
	s_nop 1
	global_atomic_add v0, v1, s[8:9]
	buffer_inv sc1
